# GEMM phases: static priority raise moved to the older half (waves 0-3) instead of waves 4-7
# speedup vs baseline: 1.0026x; 1.0026x over previous
.LBB0_129:
	s_andn2_b64 vcc, exec, s[0:1]
	s_cbranch_vccnz .LBB0_231
	v_bfe_i32 v2, v182, 27, 1
	v_lshlrev_b32_e32 v0, 4, v182
	v_lshrrev_b32_e32 v2, 22, v2
	v_add_u32_e32 v2, v0, v2
	v_and_b32_e32 v2, 0xfffffc00, v2
	v_sub_u32_e32 v2, v0, v2
	s_waitcnt vmcnt(0)
	v_ashrrev_i32_e32 v1, 31, v182
	v_lshrrev_b32_e32 v3, 4, v2
	v_lshrrev_b32_e32 v1, 26, v1
	v_bitop3_b32 v2, v3, v2, 32 bitop3:0x6c
	v_add_u32_e32 v1, v182, v1
	s_waitcnt vmcnt(17)
	v_ashrrev_i32_e32 v4, 31, v2
	v_ashrrev_i32_e32 v1, 6, v1
	v_lshrrev_b32_e32 v4, 26, v4
	v_lshlrev_b32_e32 v3, 3, v1
	v_add_u32_e32 v4, v2, v4
	v_and_b32_e32 v3, -16, v3
	v_ashrrev_i32_e32 v5, 6, v4
	v_lshlrev_b32_e32 v1, 5, v1
	v_add_u32_e32 v3, v5, v3
	v_and_b32_e32 v12, 32, v1
	v_and_b32_e32 v1, 0xc0, v4
	v_sub_u32_e32 v1, v2, v1
	v_lshlrev_b32_e32 v2, 1, v3
	v_lshrrev_b32_e32 v4, 2, v3
	v_and_b32_e32 v5, 3, v5
	s_mov_b32 s1, 0x7fffffe0
	v_ashrrev_i16_sdwa v1, v226, sext(v1) dst_sel:DWORD dst_unused:UNUSED_PAD src0_sel:DWORD src1_sel:BYTE_0
	v_and_b32_e32 v2, 24, v2
	v_and_b32_e32 v4, 4, v4
	v_and_or_b32 v5, v3, s1, v5
	v_bfe_i32 v13, v1, 0, 16
	v_or3_b32 v2, v5, v4, v2
	v_add_u32_e32 v1, v12, v13
	v_mul_lo_u32 v14, s7, v3
	v_mul_lo_u32 v2, s7, v2
	v_add_u32_e32 v0, 0x2000, v0
	v_add_lshl_u32 v184, v14, v1, 1
	v_add_lshl_u32 v186, v2, v1, 1
	v_ashrrev_i32_e32 v1, 31, v0
	v_lshrrev_b32_e32 v1, 22, v1
	v_add_u32_e32 v1, v0, v1
	v_ashrrev_i32_e32 v1, 10, v1
	v_mul_i32_i24_e32 v2, 0x400, v1
	v_sub_u32_e32 v0, v0, v2
	v_lshrrev_b32_e32 v2, 4, v0
	v_bitop3_b32 v0, v2, v0, 32 bitop3:0x6c
	v_ashrrev_i32_e32 v3, 31, v0
	s_lshl_b32 s98, s7, 8
	s_mov_b32 s99, s81
	v_lshrrev_b32_e32 v3, 26, v3
	s_lshl_b64 s[36:37], s[98:99], 1
	s_ashr_i32 s4, s19, 31
	v_lshlrev_b32_e32 v2, 3, v1
	v_add_u32_e32 v3, v0, v3
	s_mul_i32 s4, s36, s4
	s_mul_hi_u32 s5, s36, s19
	s_ashr_i32 s8, s18, 31
	v_and_b32_e32 v2, -16, v2
	v_ashrrev_i32_e32 v4, 6, v3
	s_add_i32 s4, s5, s4
	s_bfe_u32 s5, s7, 0x10017
	s_mul_i32 s8, s36, s8
	s_mul_hi_u32 s9, s36, s18
	s_ashr_i32 s0, s12, 6
	v_add_u32_e32 v2, v4, v2
	v_lshlrev_b32_e32 v1, 5, v1
	v_and_b32_e32 v4, 3, v4
	s_mul_i32 s6, s5, s19
	s_add_i32 s8, s9, s8
	s_mul_i32 s5, s5, s18
	v_and_b32_e32 v15, 32, v1
	v_and_b32_e32 v1, 0xc0, v3
	v_and_or_b32 v4, v2, s1, v4
	s_ashr_i32 s1, s12, 8
	s_lshl_b32 s33, s0, 10
	s_add_i32 s4, s4, s6
	s_add_i32 s8, s8, s5
	s_mul_i32 s5, s36, s18
	v_sub_u32_e32 v0, v0, v1
	v_lshlrev_b32_e32 v1, 1, v2
	v_lshrrev_b32_e32 v3, 2, v2
	s_add_u32 s68, s88, s5
	v_ashrrev_i16_sdwa v0, v226, sext(v0) dst_sel:DWORD dst_unused:UNUSED_PAD src0_sel:DWORD src1_sel:BYTE_0
	v_and_b32_e32 v1, 24, v1
	v_and_b32_e32 v3, 4, v3
	s_addc_u32 s69, s89, s8
	s_add_i32 s76, s33, 0
	v_bfe_i32 v16, v0, 0, 16
	v_or3_b32 v1, v4, v3, v1
	s_add_i32 m0, s76, 0x10000
	v_add_u32_e32 v0, v15, v16
	v_mul_lo_u32 v1, s7, v1
	s_mul_i32 s6, s36, s19
	global_load_lds_dwordx4 v186, s[68:69]
	s_add_i32 m0, s76, 0x12000
	v_add_lshl_u32 v190, v1, v0, 1
	s_add_u32 s70, s84, s6
	v_mul_lo_u32 v17, s7, v2
	global_load_lds_dwordx4 v190, s[68:69]
	s_addc_u32 s71, s85, s4
	s_mov_b32 m0, s76
	s_add_i32 s4, s76, 0x2000
	v_add_lshl_u32 v188, v17, v0, 1
	global_load_lds_dwordx4 v184, s[70:71]
	s_mov_b32 m0, s4
	s_add_u32 s8, s68, s98
	global_load_lds_dwordx4 v188, s[70:71]
	s_addc_u32 s9, s69, 0
	s_add_i32 m0, s76, 0x14000
	v_mov_b32_e32 v187, v180
	v_mov_b32_e32 v191, v180
	global_load_lds_dwordx4 v186, s[8:9]
	s_add_i32 m0, s76, 0x16000
	s_waitcnt vmcnt(5)
	v_lshl_add_u64 v[8:9], s[8:9], 0, v[186:187]
	v_lshl_add_u64 v[10:11], s[8:9], 0, v[190:191]
	global_load_lds_dwordx4 v190, s[8:9]
	s_add_u32 s8, s70, s98
	s_addc_u32 s9, s71, 0
	s_add_i32 s5, s76, 0x4000
	s_mov_b32 m0, s5
	s_add_i32 s6, s76, 0x6000
	global_load_lds_dwordx4 v184, s[8:9]
	s_mov_b32 m0, s6
	s_load_dword s74, s[24:25], 0x0
	global_load_lds_dwordx4 v188, s[8:9]
	v_mov_b32_e32 v185, v180
	v_mov_b32_e32 v189, v180
	v_lshl_add_u64 v[0:1], s[68:69], 0, v[186:187]
	v_lshl_add_u64 v[2:3], s[68:69], 0, v[190:191]
	v_lshl_add_u64 v[4:5], s[70:71], 0, v[184:185]
	v_lshl_add_u64 v[6:7], s[70:71], 0, v[188:189]
	s_setprio 1
	s_cmp_lg_u32 s1, 1
	v_writelane_b32 v240, s12, 12
	s_cbranch_scc1 .LBB0_132
	s_setprio 0
	s_barrier
